# P13 final output stores: nt (streaming) so the end-of-kernel dirty tail is smaller
# speedup vs baseline: 1.0062x; 1.0062x over previous
; __device__ __forceinline__ v4u pack8(const float (&f)[8]) { v4u w; w.x = pk2(f[0], f[1]); w.y = pk2(f[2], f[3]); w.z = pk2(f[4], f[5]); w.w = pk2(f[6], f[7]); return w; }
; template <bool OUT_F32, bool HAS_NEXT>
; __device__ __forceinline__ void norm_res_phase(const bf16* resH, const bf16* Y, const float* gpost, float scale, bf16* hout, float* fout, float* RS, int gw, int NGW, int lane) {
;     ...
;     auto ld = [&](int r, v4u (&yv)[2], v4u (&hv)[2]) {
; #pragma unroll
;         for (int c = 0; c < 2; ++c) { const int col = 512 * c + 8 * lane;
;             yv[c] = __builtin_nontemporal_load((const v4u*)(Y + (size_t)r * D + col));
;             hv[c] = *(const v4u*)(resH + (size_t)r * D + col); } };
;     auto fin = [&](int r, const v4u (&yv)[2], const v4u (&hv)[2]) {
;         float y[2][8], h[2][8]; float ss = 0.f;
; #pragma unroll
;         for (int c = 0; c < 2; ++c) { unpack8(yv[c], y[c]); unpack8(hv[c], h[c]);
; #pragma unroll
;             for (int e = 0; e < 8; ++e) ss += y[c][e] * y[c][e]; }
;         const float rstd = scale / sqrtf(wave_sum(ss) * (1.f / D) + EPS);
;         float s2 = 0.f;
; #pragma unroll
;         for (int c = 0; c < 2; ++c) {
;             const int col = 512 * c + 8 * lane;
; #pragma unroll
;             for (int e = 0; e < 8; ++e) { h[c][e] += y[c][e] * rstd * gg[c][e]; s2 += h[c][e] * h[c][e]; }
;             if constexpr (OUT_F32) { float* o = fout + (size_t)r * D + col; *(float4*)o = make_float4(h[c][0], h[c][1], h[c][2], h[c][3]); *(float4*)(o + 4) = make_float4(h[c][4], h[c][5], h[c][6], h[c][7]); }
;             else *(v4u*)(hout + (size_t)r * D + col) = pack8(h[c]);
;         }
;         if constexpr (HAS_NEXT) { const float r2 = 1.f / sqrtf(wave_sum(s2) * (1.f / D) + EPS); if (lane == 0) RS[r] = r2; } };
.LBB0_1726:
	s_add_i32 s7, s84, s69
	s_cmpk_lt_i32 s7, 0x4200
	s_cselect_b32 s2, s7, s84
	s_ashr_i32 s3, s2, 31
	s_lshl_b64 s[0:1], s[2:3], 11
	v_lshl_add_u64 v[62:63], v[50:51], 0, s[0:1]
	v_lshl_add_u64 v[64:65], v[52:53], 0, s[0:1]
	global_load_dwordx4 v[44:47], v[62:63], off nt
	global_load_dwordx4 v[40:43], v[62:63], off offset:1024 nt
	global_load_dwordx4 v[36:39], v[64:65], off
	global_load_dwordx4 v[32:35], v[64:65], off offset:1024
	s_ashr_i32 s85, s84, 31
	s_lshl_b64 s[0:1], s[84:85], 12
	s_cmpk_gt_i32 s7, 0x41ff
	s_waitcnt vmcnt(7)
	v_lshlrev_b32_e32 v62, 16, v28
	v_and_b32_e32 v63, 0xffff0000, v28
	v_pk_mul_f32 v[64:65], v[62:63], v[62:63]
	v_lshlrev_b32_e32 v28, 16, v29
	v_and_b32_e32 v29, 0xffff0000, v29
	v_pk_mul_f32 v[66:67], v[28:29], v[28:29]
	v_add_f32_e32 v64, v64, v65
	v_lshlrev_b32_e32 v68, 16, v30
	v_and_b32_e32 v69, 0xffff0000, v30
	v_add_f32_e32 v64, v66, v64
	v_pk_mul_f32 v[70:71], v[68:69], v[68:69]
	v_add_f32_e32 v64, v67, v64
	v_lshlrev_b32_e32 v30, 16, v31
	v_and_b32_e32 v31, 0xffff0000, v31
	v_add_f32_e32 v64, v70, v64
	v_pk_mul_f32 v[72:73], v[30:31], v[30:31]
	v_add_f32_e32 v64, v71, v64
	s_waitcnt vmcnt(6)
	v_lshlrev_b32_e32 v74, 16, v24
	v_and_b32_e32 v75, 0xffff0000, v24
	v_add_f32_e32 v64, v72, v64
	v_pk_mul_f32 v[76:77], v[74:75], v[74:75]
	v_add_f32_e32 v64, v73, v64
	v_lshlrev_b32_e32 v24, 16, v25
	v_and_b32_e32 v25, 0xffff0000, v25
	v_add_f32_e32 v64, v76, v64
	v_pk_mul_f32 v[78:79], v[24:25], v[24:25]
	v_add_f32_e32 v64, v77, v64
	v_lshlrev_b32_e32 v80, 16, v26
	v_and_b32_e32 v81, 0xffff0000, v26
	v_add_f32_e32 v64, v78, v64
	v_pk_mul_f32 v[82:83], v[80:81], v[80:81]
	v_add_f32_e32 v64, v79, v64
	v_lshlrev_b32_e32 v26, 16, v27
	v_and_b32_e32 v27, 0xffff0000, v27
	v_add_f32_e32 v64, v82, v64
	v_pk_mul_f32 v[84:85], v[26:27], v[26:27]
	v_add_f32_e32 v64, v83, v64
	v_add_f32_e32 v64, v84, v64
	v_add_f32_e32 v64, v85, v64
	ds_bpermute_b32 v65, v54, v64
	s_waitcnt vmcnt(4)
	v_lshlrev_b32_e32 v78, 16, v18
	v_and_b32_e32 v83, 0xffff0000, v19
	v_lshlrev_b32_e32 v66, 16, v20
	v_and_b32_e32 v67, 0xffff0000, v20
	s_waitcnt lgkmcnt(0)
	v_add_f32_e32 v64, v64, v65
	ds_bpermute_b32 v65, v55, v64
	v_lshlrev_b32_e32 v20, 16, v21
	v_and_b32_e32 v21, 0xffff0000, v21
	v_readfirstlane_b32 s6, v0
	s_waitcnt lgkmcnt(0)
	v_add_f32_e32 v64, v64, v65
	ds_bpermute_b32 v65, v56, v64
	s_waitcnt lgkmcnt(0)
	v_add_f32_e32 v70, v64, v65
	ds_bpermute_b32 v71, v57, v70
	v_lshl_add_u64 v[64:65], v[48:49], 0, s[0:1]
	s_waitcnt lgkmcnt(0)
	v_add_f32_e32 v72, v70, v71
	ds_bpermute_b32 v73, v58, v72
	v_lshlrev_b32_e32 v70, 16, v22
	v_and_b32_e32 v71, 0xffff0000, v22
	v_lshlrev_b32_e32 v22, 16, v23
	v_and_b32_e32 v23, 0xffff0000, v23
	s_waitcnt lgkmcnt(0)
	v_add_f32_e32 v76, v72, v73
	ds_bpermute_b32 v77, v59, v76
	v_lshlrev_b32_e32 v72, 16, v16
	v_and_b32_e32 v73, 0xffff0000, v16
	s_waitcnt lgkmcnt(0)
	v_add_f32_e32 v16, v76, v77
	v_fmamk_f32 v16, v16, 0x3a800000, v60
	v_mul_f32_e32 v76, 0x4f800000, v16
	v_cmp_gt_f32_e32 vcc, s5, v16
	v_and_b32_e32 v77, 0xffff0000, v17
	s_nop 0
	v_cndmask_b32_e32 v16, v16, v76, vcc
	v_sqrt_f32_e32 v79, v16
	v_lshlrev_b32_e32 v76, 16, v17
	v_add_u32_e32 v17, -1, v79
	v_fma_f32 v82, -v17, v79, v16
	v_cmp_ge_f32_e64 s[0:1], 0, v82
	v_add_u32_e32 v82, 1, v79
	s_nop 0
	v_cndmask_b32_e64 v17, v79, v17, s[0:1]
	v_fma_f32 v79, -v82, v79, v16
	v_cmp_lt_f32_e64 s[0:1], 0, v79
	s_nop 1
	v_cndmask_b32_e64 v17, v17, v82, s[0:1]
	v_mul_f32_e32 v79, 0x37800000, v17
	v_cndmask_b32_e32 v17, v17, v79, vcc
	v_cmp_class_f32_e32 vcc, v16, v61
	v_and_b32_e32 v79, 0xffff0000, v18
	v_lshlrev_b32_e32 v82, 16, v19
	v_cndmask_b32_e32 v16, v17, v16, vcc
	v_div_scale_f32 v17, s[0:1], v16, v16, 0.5
	v_rcp_f32_e32 v84, v17
	s_mov_b64 s[0:1], -1
	v_fma_f32 v18, -v17, v84, 1.0
	v_fmac_f32_e32 v84, v18, v84
	v_div_scale_f32 v18, vcc, 0.5, v16, 0.5
	v_mul_f32_e32 v19, v18, v84
	v_fma_f32 v85, -v17, v19, v18
	v_fmac_f32_e32 v19, v85, v84
	v_fma_f32 v17, -v17, v19, v18
	v_div_fmas_f32 v17, v17, v84, v19
	v_div_fixup_f32 v84, v17, v16, 0.5
	v_pk_mul_f32 v[18:19], v[84:85], v[28:29] op_sel_hi:[0,1]
	v_pk_mul_f32 v[16:17], v[84:85], v[62:63] op_sel_hi:[0,1]
	v_pk_fma_f32 v[18:19], v[6:7], v[18:19], v[20:21]
	v_pk_mul_f32 v[20:21], v[84:85], v[68:69] op_sel_hi:[0,1]
	v_pk_mul_f32 v[28:29], v[84:85], v[30:31] op_sel_hi:[0,1]
	v_pk_fma_f32 v[16:17], v[4:5], v[16:17], v[66:67]
	v_pk_fma_f32 v[20:21], v[0:1], v[20:21], v[70:71]
	v_pk_fma_f32 v[22:23], v[2:3], v[28:29], v[22:23]
	global_store_dwordx4 v[64:65], v[16:19], off nt
	global_store_dwordx4 v[64:65], v[20:23], off offset:16 nt
	s_nop 0
	v_pk_mul_f32 v[16:17], v[84:85], v[74:75] op_sel_hi:[0,1]
	v_pk_mul_f32 v[18:19], v[84:85], v[24:25] op_sel_hi:[0,1]
	v_pk_mul_f32 v[20:21], v[84:85], v[80:81] op_sel_hi:[0,1]
	v_pk_mul_f32 v[22:23], v[84:85], v[26:27] op_sel_hi:[0,1]
	v_pk_fma_f32 v[16:17], v[12:13], v[16:17], v[72:73]
	v_pk_fma_f32 v[18:19], v[14:15], v[18:19], v[76:77]
	v_pk_fma_f32 v[20:21], v[8:9], v[20:21], v[78:79]
	v_pk_fma_f32 v[22:23], v[10:11], v[22:23], v[82:83]
	global_store_dwordx4 v[64:65], v[16:19], off offset:2048 nt
	global_store_dwordx4 v[64:65], v[20:23], off offset:2064 nt
	s_cbranch_scc1 .LBB0_1725
; __device__ __forceinline__ v4u pack8(const float (&f)[8]) { v4u w; w.x = pk2(f[0], f[1]); w.y = pk2(f[2], f[3]); w.z = pk2(f[4], f[5]); w.w = pk2(f[6], f[7]); return w; }
; template <bool OUT_F32, bool HAS_NEXT>
; __device__ __forceinline__ void norm_res_phase(const bf16* resH, const bf16* Y, const float* gpost, float scale, bf16* hout, float* fout, float* RS, int gw, int NGW, int lane) {
;     ...
;     auto ld = [&](int r, v4u (&yv)[2], v4u (&hv)[2]) {
; #pragma unroll
;         for (int c = 0; c < 2; ++c) { const int col = 512 * c + 8 * lane;
;             yv[c] = __builtin_nontemporal_load((const v4u*)(Y + (size_t)r * D + col));
;             hv[c] = *(const v4u*)(resH + (size_t)r * D + col); } };
;     auto fin = [&](int r, const v4u (&yv)[2], const v4u (&hv)[2]) {
;         float y[2][8], h[2][8]; float ss = 0.f;
; #pragma unroll
;         for (int c = 0; c < 2; ++c) { unpack8(yv[c], y[c]); unpack8(hv[c], h[c]);
; #pragma unroll
;             for (int e = 0; e < 8; ++e) ss += y[c][e] * y[c][e]; }
;         const float rstd = scale / sqrtf(wave_sum(ss) * (1.f / D) + EPS);
;         float s2 = 0.f;
; #pragma unroll
;         for (int c = 0; c < 2; ++c) {
;             const int col = 512 * c + 8 * lane;
; #pragma unroll
;             for (int e = 0; e < 8; ++e) { h[c][e] += y[c][e] * rstd * gg[c][e]; s2 += h[c][e] * h[c][e]; }
;             if constexpr (OUT_F32) { float* o = fout + (size_t)r * D + col; *(float4*)o = make_float4(h[c][0], h[c][1], h[c][2], h[c][3]); *(float4*)(o + 4) = make_float4(h[c][4], h[c][5], h[c][6], h[c][7]); }
;             else *(v4u*)(hout + (size_t)r * D + col) = pack8(h[c]);
;         }
;         if constexpr (HAS_NEXT) { const float r2 = 1.f / sqrtf(wave_sum(s2) * (1.f / D) + EPS); if (lane == 0) RS[r] = r2; } };
	s_add_i32 s6, s7, s69
	s_add_i32 s0, s4, s84
	s_cmpk_lt_i32 s0, 0x4200
	s_cselect_b32 s0, s0, s7
	s_ashr_i32 s1, s0, 31
	s_lshl_b64 s[0:1], s[0:1], 11
	v_lshl_add_u64 v[62:63], v[50:51], 0, s[0:1]
	v_lshl_add_u64 v[64:65], v[52:53], 0, s[0:1]
	global_load_dwordx4 v[28:31], v[62:63], off nt
	global_load_dwordx4 v[24:27], v[62:63], off offset:1024 nt
	global_load_dwordx4 v[20:23], v[64:65], off
	global_load_dwordx4 v[16:19], v[64:65], off offset:1024
	s_waitcnt vmcnt(11)
	v_lshlrev_b32_e32 v62, 16, v44
	v_and_b32_e32 v63, 0xffff0000, v44
	v_pk_mul_f32 v[64:65], v[62:63], v[62:63]
	v_lshlrev_b32_e32 v44, 16, v45
	v_and_b32_e32 v45, 0xffff0000, v45
	v_pk_mul_f32 v[66:67], v[44:45], v[44:45]
	v_add_f32_e32 v64, v64, v65
	v_lshlrev_b32_e32 v68, 16, v46
	v_and_b32_e32 v69, 0xffff0000, v46
	v_add_f32_e32 v64, v66, v64
	v_pk_mul_f32 v[70:71], v[68:69], v[68:69]
	v_add_f32_e32 v64, v67, v64
	v_lshlrev_b32_e32 v46, 16, v47
	v_and_b32_e32 v47, 0xffff0000, v47
	v_add_f32_e32 v64, v70, v64
	v_pk_mul_f32 v[72:73], v[46:47], v[46:47]
	v_add_f32_e32 v64, v71, v64
	s_waitcnt vmcnt(10)
	v_lshlrev_b32_e32 v74, 16, v40
	v_and_b32_e32 v75, 0xffff0000, v40
	v_add_f32_e32 v64, v72, v64
	v_pk_mul_f32 v[76:77], v[74:75], v[74:75]
	v_add_f32_e32 v64, v73, v64
	v_lshlrev_b32_e32 v40, 16, v41
	v_and_b32_e32 v41, 0xffff0000, v41
	v_add_f32_e32 v64, v76, v64
	v_pk_mul_f32 v[78:79], v[40:41], v[40:41]
	v_add_f32_e32 v64, v77, v64
	v_lshlrev_b32_e32 v80, 16, v42
	v_and_b32_e32 v81, 0xffff0000, v42
	v_add_f32_e32 v64, v78, v64
	v_pk_mul_f32 v[82:83], v[80:81], v[80:81]
	v_add_f32_e32 v64, v79, v64
	v_lshlrev_b32_e32 v42, 16, v43
	v_and_b32_e32 v43, 0xffff0000, v43
	v_add_f32_e32 v64, v82, v64
	v_pk_mul_f32 v[84:85], v[42:43], v[42:43]
	v_add_f32_e32 v64, v83, v64
	v_add_f32_e32 v64, v84, v64
	v_add_f32_e32 v64, v85, v64
	ds_bpermute_b32 v65, v54, v64
	s_lshl_b64 s[0:1], s[2:3], 12
	s_waitcnt vmcnt(8)
	v_lshlrev_b32_e32 v78, 16, v34
	v_and_b32_e32 v83, 0xffff0000, v35
	v_lshlrev_b32_e32 v66, 16, v36
	s_waitcnt lgkmcnt(0)
	v_add_f32_e32 v64, v64, v65
	ds_bpermute_b32 v65, v55, v64
	v_and_b32_e32 v67, 0xffff0000, v36
	v_lshlrev_b32_e32 v36, 16, v37
	v_and_b32_e32 v37, 0xffff0000, v37
	s_cmpk_gt_i32 s6, 0x41ff
	s_waitcnt lgkmcnt(0)
	v_add_f32_e32 v64, v64, v65
	ds_bpermute_b32 v65, v56, v64
	s_waitcnt lgkmcnt(0)
	v_add_f32_e32 v70, v64, v65
	ds_bpermute_b32 v71, v57, v70
	v_lshl_add_u64 v[64:65], v[48:49], 0, s[0:1]
	s_waitcnt lgkmcnt(0)
	v_add_f32_e32 v72, v70, v71
	ds_bpermute_b32 v73, v58, v72
	v_lshlrev_b32_e32 v70, 16, v38
	v_and_b32_e32 v71, 0xffff0000, v38
	v_lshlrev_b32_e32 v38, 16, v39
	v_and_b32_e32 v39, 0xffff0000, v39
	s_waitcnt lgkmcnt(0)
	v_add_f32_e32 v76, v72, v73
	ds_bpermute_b32 v77, v59, v76
	v_lshlrev_b32_e32 v72, 16, v32
	v_and_b32_e32 v73, 0xffff0000, v32
	s_waitcnt lgkmcnt(0)
	v_add_f32_e32 v32, v76, v77
	v_fmamk_f32 v32, v32, 0x3a800000, v60
	v_mul_f32_e32 v76, 0x4f800000, v32
	v_cmp_gt_f32_e32 vcc, s5, v32
	v_and_b32_e32 v77, 0xffff0000, v33
	s_nop 0
	v_cndmask_b32_e32 v32, v32, v76, vcc
	v_sqrt_f32_e32 v79, v32
	v_lshlrev_b32_e32 v76, 16, v33
	v_add_u32_e32 v33, -1, v79
	v_fma_f32 v82, -v33, v79, v32
	v_cmp_ge_f32_e64 s[0:1], 0, v82
	v_add_u32_e32 v82, 1, v79
	s_nop 0
	v_cndmask_b32_e64 v33, v79, v33, s[0:1]
	v_fma_f32 v79, -v82, v79, v32
	v_cmp_lt_f32_e64 s[0:1], 0, v79
	s_nop 1
	v_cndmask_b32_e64 v33, v33, v82, s[0:1]
	v_mul_f32_e32 v79, 0x37800000, v33
	v_cndmask_b32_e32 v33, v33, v79, vcc
	v_cmp_class_f32_e32 vcc, v32, v61
	v_and_b32_e32 v79, 0xffff0000, v34
	v_lshlrev_b32_e32 v82, 16, v35
	v_cndmask_b32_e32 v32, v33, v32, vcc
	v_div_scale_f32 v33, s[0:1], v32, v32, 0.5
	v_rcp_f32_e32 v84, v33
	s_cselect_b64 s[0:1], -1, 0
	v_fma_f32 v34, -v33, v84, 1.0
	v_fmac_f32_e32 v84, v34, v84
	v_div_scale_f32 v34, vcc, 0.5, v32, 0.5
	v_mul_f32_e32 v35, v34, v84
	v_fma_f32 v85, -v33, v35, v34
	v_fmac_f32_e32 v35, v85, v84
	v_fma_f32 v33, -v33, v35, v34
	v_div_fmas_f32 v33, v33, v84, v35
	v_div_fixup_f32 v84, v33, v32, 0.5
	v_pk_mul_f32 v[32:33], v[84:85], v[62:63] op_sel_hi:[0,1]
	v_pk_mul_f32 v[34:35], v[84:85], v[44:45] op_sel_hi:[0,1]
	v_pk_fma_f32 v[32:33], v[4:5], v[32:33], v[66:67]
	v_pk_fma_f32 v[34:35], v[6:7], v[34:35], v[36:37]
	v_pk_mul_f32 v[36:37], v[84:85], v[68:69] op_sel_hi:[0,1]
	v_pk_mul_f32 v[44:45], v[84:85], v[46:47] op_sel_hi:[0,1]
	v_pk_fma_f32 v[36:37], v[0:1], v[36:37], v[70:71]
	v_pk_fma_f32 v[38:39], v[2:3], v[44:45], v[38:39]
	global_store_dwordx4 v[64:65], v[32:35], off nt
	global_store_dwordx4 v[64:65], v[36:39], off offset:16 nt
	s_nop 0
	v_pk_mul_f32 v[32:33], v[84:85], v[74:75] op_sel_hi:[0,1]
	v_pk_mul_f32 v[34:35], v[84:85], v[40:41] op_sel_hi:[0,1]
	v_pk_fma_f32 v[32:33], v[12:13], v[32:33], v[72:73]
	v_pk_fma_f32 v[34:35], v[14:15], v[34:35], v[76:77]
	v_pk_mul_f32 v[36:37], v[84:85], v[80:81] op_sel_hi:[0,1]
	v_pk_mul_f32 v[38:39], v[84:85], v[42:43] op_sel_hi:[0,1]
	v_pk_fma_f32 v[36:37], v[8:9], v[36:37], v[78:79]
	v_pk_fma_f32 v[38:39], v[10:11], v[38:39], v[82:83]
	global_store_dwordx4 v[64:65], v[32:35], off offset:2048 nt
	global_store_dwordx4 v[64:65], v[36:39], off offset:2064 nt
	s_branch .LBB0_1725
